# ua done-counter spin: poll interval s_sleep 2 -> 40 to reduce polling interference with the critical GLA chains
# speedup vs baseline: 1.0039x; 1.0039x over previous
; __device__ __forceinline__ unsigned xb_ld(unsigned* p)              { return __hip_atomic_load(p, __ATOMIC_RELAXED, __HIP_MEMORY_SCOPE_AGENT); }
; __global__ void __launch_bounds__(512, 2) hybrid_fwd(Args args) {
;     ...
;                         if (tid == 0 && !((MISC[2] >> bq) & 1)) {
;                             unsigned sp = 0; while (xb_ld(done + 64 * bq) < 8u) { __builtin_amdgcn_s_sleep(2); if (++sp > (1u << 24)) break; }
;                             __builtin_amdgcn_fence(__ATOMIC_ACQUIRE, "agent"); asm volatile("s_waitcnt vmcnt(0)" ::: "memory");
;                             MISC[2] = MISC[2] | (1 << bq); }
.LBB0_219:
	global_load_dword v0, v1, s[4:5] sc1
	s_mov_b64 s[2:3], -1
	s_waitcnt vmcnt(0)
	v_cmp_lt_u32_e32 vcc, 7, v0
	s_cbranch_vccnz .LBB0_218
	s_cmp_lg_u32 s8, 0
	s_sleep 40
	s_cbranch_scc0 .LBB0_217
	global_load_dword v0, v1, s[4:5] sc1
	s_waitcnt vmcnt(0)
	v_cmp_gt_u32_e32 vcc, 8, v0
	s_cbranch_vccz .LBB0_218
	s_sleep 40
	global_load_dword v0, v1, s[4:5] sc1
	s_waitcnt vmcnt(0)
	v_cmp_gt_u32_e32 vcc, 8, v0
	s_cbranch_vccz .LBB0_218
	s_sleep 40
	global_load_dword v0, v1, s[4:5] sc1
	s_waitcnt vmcnt(0)
	v_cmp_gt_u32_e32 vcc, 8, v0
	s_cbranch_vccz .LBB0_218
	s_sleep 40
	global_load_dword v0, v1, s[4:5] sc1
	s_waitcnt vmcnt(0)
	v_cmp_gt_u32_e32 vcc, 8, v0
	s_cbranch_vccz .LBB0_218
	s_sleep 40
	global_load_dword v0, v1, s[4:5] sc1
	s_waitcnt vmcnt(0)
	v_cmp_gt_u32_e32 vcc, 8, v0
	s_cbranch_vccz .LBB0_218
	s_sleep 40
	global_load_dword v0, v1, s[4:5] sc1
	s_waitcnt vmcnt(0)
	v_cmp_gt_u32_e32 vcc, 8, v0
	s_cbranch_vccz .LBB0_218
	s_sleep 40
	global_load_dword v0, v1, s[4:5] sc1
	s_waitcnt vmcnt(0)
	v_cmp_gt_u32_e32 vcc, 8, v0
	s_cbranch_vccz .LBB0_218
	s_sleep 40
	s_add_i32 s8, s8, -8
	s_mov_b64 s[2:3], 0
	s_branch .LBB0_218
